# foxc prefix phase: all loads of two work items issued together (counted vmcnt), third-round items moved to non-scan waves
# speedup vs baseline: 1.0103x; 1.0015x over previous
.LBB0_208:
	s_or_b64 exec, exec, s[0:1]
	s_barrier
	s_mov_b64 s[0:1], exec
	v_readlane_b32 s2, v245, 45
	v_readlane_b32 s3, v245, 46
	s_and_b64 s[2:3], s[0:1], s[2:3]
	s_mov_b64 exec, s[2:3]
	s_cbranch_execz .LBB0_219
	v_and_b32_e32 v0, 64, v224
	v_add_u32_e32 v1, 64, v0
	v_xor_b32_e32 v2, 32, v224
	v_cmp_lt_i32_e32 vcc, v2, v1
	v_xor_b32_e32 v3, 16, v224
	v_xor_b32_e32 v4, 8, v224
	v_cndmask_b32_e32 v2, v224, v2, vcc
	v_cmp_lt_i32_e32 vcc, v3, v1
	v_xor_b32_e32 v5, 4, v224
	v_xor_b32_e32 v6, 2, v224
	v_cndmask_b32_e32 v3, v224, v3, vcc
	v_cmp_lt_i32_e32 vcc, v4, v1
	v_xor_b32_e32 v7, 1, v224
	v_readlane_b32 s2, v245, 61
	v_cndmask_b32_e32 v4, v224, v4, vcc
	v_cmp_lt_i32_e32 vcc, v5, v1
	v_lshlrev_b32_e32 v2, 2, v2
	v_lshlrev_b32_e32 v3, 2, v3
	v_cndmask_b32_e32 v5, v224, v5, vcc
	v_cmp_lt_i32_e32 vcc, v6, v1
	v_lshlrev_b32_e32 v4, 2, v4
	v_lshlrev_b32_e32 v5, 2, v5
	v_cndmask_b32_e32 v6, v224, v6, vcc
	v_cmp_lt_i32_e32 vcc, v7, v1
	v_lshlrev_b32_e32 v6, 2, v6
	s_lshl_b32 s8, s2, 3
	v_cndmask_b32_e32 v1, v224, v7, vcc
	v_lshlrev_b32_e32 v7, 2, v1
	v_add_u32_e32 v1, -1, v224
	v_cmp_lt_i32_e32 vcc, v1, v0
	s_mov_b64 s[2:3], 0
	v_mov_b32_e32 v14, v214
	v_cndmask_b32_e32 v1, v1, v224, vcc
	v_lshlrev_b32_e32 v8, 2, v1
	v_add_u32_e32 v1, -2, v224
	v_cmp_lt_i32_e32 vcc, v1, v0
	s_nop 1
	v_cndmask_b32_e32 v1, v1, v224, vcc
	v_lshlrev_b32_e32 v9, 2, v1
	v_add_u32_e32 v1, -4, v224
	v_cmp_lt_i32_e32 vcc, v1, v0
	s_nop 1
	v_cndmask_b32_e32 v1, v1, v224, vcc
	v_lshlrev_b32_e32 v10, 2, v1
	v_add_u32_e32 v1, -8, v224
	v_cmp_lt_i32_e32 vcc, v1, v0
	s_nop 1
	v_cndmask_b32_e32 v1, v1, v224, vcc
	v_lshlrev_b32_e32 v11, 2, v1
	v_add_u32_e32 v1, -16, v224
	v_cmp_lt_i32_e32 vcc, v1, v0
	s_nop 1
	v_cndmask_b32_e32 v1, v1, v224, vcc
	v_lshlrev_b32_e32 v12, 2, v1
	v_subrev_u32_e32 v1, 32, v224
	v_cmp_lt_i32_e32 vcc, v1, v0
	s_nop 1
	v_cndmask_b32_e32 v0, v1, v224, vcc
	v_lshlrev_b32_e32 v13, 2, v0
	v_add_u32_e32 v14, 0x3c0, v214
	v_and_b32_e32 v14, 0x7ff, v14
	v_readlane_b32 s68, v245, 34
	v_readlane_b32 s69, v245, 35
	v_readlane_b32 s70, v245, 10
	v_readlane_b32 s71, v245, 11
	v_readlane_b32 s72, v245, 63
	v_readlane_b32 s73, v244, 0
	v_readlane_b32 s74, v244, 1
	v_readlane_b32 s75, v244, 2
	v_readlane_b32 s76, v244, 3
	v_readlane_b32 s77, v244, 4
	v_readlane_b32 s78, v244, 5
	v_readlane_b32 s79, v244, 6
	v_readlane_b32 s80, v244, 7
	v_readlane_b32 s81, v244, 8
	v_readlane_b32 s82, v244, 9
	v_readlane_b32 s83, v244, 10
	s_movk_i32 s9, 0x2080
.Lfc_loop:
	v_mul_u32_u24_sdwa v23, v14, s16 dst_sel:DWORD dst_unused:UNUSED_PAD src0_sel:WORD_0 src1_sel:DWORD
	v_lshrrev_b32_e32 v15, 19, v23
	v_mul_lo_u16_e32 v23, 0x82, v15
	v_sub_u16_e32 v16, v14, v23
	v_mul_u32_u24_e32 v23, 0x82, v15
	v_add_lshl_u32 v178, v23, v176, 2
	v_lshrrev_b32_e32 v23, 3, v15
	v_and_b32_e32 v24, 7, v15
	v_lshl_add_u64 v[26:27], s[68:69], 0, v[178:179]
	v_lshl_or_b32 v0, v16, 6, v176
	global_load_dword v20, v[26:27], off
	global_load_dword v21, v[26:27], off offset:256
	global_load_dword v22, v[26:27], off offset:512
	v_mad_u32_u24 v23, v23, s9, v0
	v_mul_u32_u24_e32 v23, 0x1618, v23
	v_or_b32_e32 v178, v23, v24
	v_lshl_add_u64 v[26:27], v[178:179], 1, s[56:57]
	v_or_b32_e32 v178, s8, v24
	global_load_ushort v25, v[26:27], off offset:3072
	v_lshl_add_u64 v[26:27], v[178:179], 2, s[70:71]
	global_load_dword v26, v[26:27], off
	v_add_u32_e32 v28, s33, v14
	s_nop 0
	v_readfirstlane_b32 s6, v28
	s_cmp_le_u32 s6, s37
	s_cselect_b32 s7, 1, 0
	s_min_u32 s6, s6, s37
	v_mov_b32_e32 v28, s6
	v_mul_u32_u24_sdwa v37, v28, s16 dst_sel:DWORD dst_unused:UNUSED_PAD src0_sel:WORD_0 src1_sel:DWORD
	v_lshrrev_b32_e32 v29, 19, v37
	v_mul_lo_u16_e32 v37, 0x82, v29
	v_sub_u16_e32 v30, v28, v37
	v_mul_u32_u24_e32 v37, 0x82, v29
	v_add_lshl_u32 v178, v37, v176, 2
	v_lshrrev_b32_e32 v37, 3, v29
	v_and_b32_e32 v38, 7, v29
	v_lshl_add_u64 v[40:41], s[68:69], 0, v[178:179]
	v_lshl_or_b32 v31, v30, 6, v176
	global_load_dword v32, v[40:41], off
	global_load_dword v33, v[40:41], off offset:256
	global_load_dword v34, v[40:41], off offset:512
	v_mad_u32_u24 v37, v37, s9, v31
	v_mul_u32_u24_e32 v37, 0x1618, v37
	v_or_b32_e32 v178, v37, v38
	v_lshl_add_u64 v[40:41], v[178:179], 1, s[56:57]
	v_or_b32_e32 v178, s8, v38
	global_load_ushort v35, v[40:41], off offset:3072
	v_lshl_add_u64 v[40:41], v[178:179], 2, s[70:71]
	global_load_dword v36, v[40:41], off
	s_waitcnt vmcnt(7)
	v_cmp_lt_u32_e32 vcc, v176, v16
	s_nop 1
	v_cndmask_b32_e32 v17, 0, v20, vcc
	v_add_f32_e32 v17, 0, v17
	v_cmp_lt_u32_e32 vcc, v215, v16
	s_nop 1
	v_cndmask_b32_e32 v18, 0, v21, vcc
	v_add_f32_e32 v17, v17, v18
	v_cmp_lt_u32_e32 vcc, v216, v16
	s_nop 1
	v_cndmask_b32_e32 v18, 0, v22, vcc
	v_add_f32_e32 v17, v17, v18
	ds_bpermute_b32 v18, v2, v17
	s_waitcnt lgkmcnt(0)
	v_add_f32_e32 v18, v17, v18
	ds_bpermute_b32 v19, v3, v18
	s_waitcnt lgkmcnt(0)
	v_add_f32_e32 v18, v18, v19
	ds_bpermute_b32 v19, v4, v18
	s_waitcnt lgkmcnt(0)
	v_add_f32_e32 v18, v18, v19
	ds_bpermute_b32 v19, v5, v18
	s_waitcnt lgkmcnt(0)
	v_add_f32_e32 v18, v18, v19
	ds_bpermute_b32 v19, v6, v18
	s_waitcnt lgkmcnt(0)
	v_add_f32_e32 v1, v18, v19
	ds_bpermute_b32 v17, v7, v1
	s_waitcnt vmcnt(5)
	v_lshlrev_b32_e32 v25, 16, v25
	v_add_f32_e32 v25, v26, v25
	v_mul_f32_e64 v26, |v25|, s98
	v_exp_f32_e32 v26, v26
	v_min_f32_e32 v25, 0, v25
	v_add_f32_e32 v26, 1.0, v26
	v_log_f32_e32 v26, v26
	s_nop 0
	v_fmac_f32_e32 v25, 0xbf317218, v26
	v_cmp_lt_u32_e32 vcc, s46, v0
	s_nop 1
	v_cndmask_b32_e32 v16, 0, v25, vcc
	s_waitcnt lgkmcnt(0)
	v_add_f32_e32 v1, v1, v17
	ds_bpermute_b32 v17, v8, v16
	v_mul_u32_u24_e32 v15, 0x2080, v15
	s_waitcnt lgkmcnt(0)
	v_add_f32_e32 v17, v16, v17
	v_cndmask_b32_e64 v16, v17, v16, s[72:73]
	ds_bpermute_b32 v17, v9, v16
	v_add_lshl_u32 v0, v0, v15, 2
	s_waitcnt lgkmcnt(0)
	v_add_f32_e32 v17, v16, v17
	v_cndmask_b32_e64 v16, v17, v16, s[74:75]
	ds_bpermute_b32 v17, v10, v16
	s_waitcnt lgkmcnt(0)
	v_add_f32_e32 v17, v16, v17
	v_cndmask_b32_e64 v16, v17, v16, s[76:77]
	ds_bpermute_b32 v17, v11, v16
	s_waitcnt lgkmcnt(0)
	v_add_f32_e32 v17, v16, v17
	v_cndmask_b32_e64 v16, v17, v16, s[78:79]
	ds_bpermute_b32 v17, v12, v16
	s_waitcnt lgkmcnt(0)
	v_add_f32_e32 v17, v16, v17
	v_cndmask_b32_e64 v16, v17, v16, s[80:81]
	ds_bpermute_b32 v17, v13, v16
	s_waitcnt lgkmcnt(0)
	v_add_f32_e32 v17, v16, v17
	v_cndmask_b32_e64 v16, v17, v16, s[82:83]
	v_add_f32_e32 v1, v1, v16
	global_store_dword v0, v1, s[60:61]
	s_cmp_eq_u32 s7, 0
	s_cbranch_scc1 .Lfc_noB
	s_waitcnt vmcnt(3)
	v_cmp_lt_u32_e32 vcc, v176, v30
	s_nop 1
	v_cndmask_b32_e32 v17, 0, v32, vcc
	v_add_f32_e32 v17, 0, v17
	v_cmp_lt_u32_e32 vcc, v215, v30
	s_nop 1
	v_cndmask_b32_e32 v18, 0, v33, vcc
	v_add_f32_e32 v17, v17, v18
	v_cmp_lt_u32_e32 vcc, v216, v30
	s_nop 1
	v_cndmask_b32_e32 v18, 0, v34, vcc
	v_add_f32_e32 v17, v17, v18
	ds_bpermute_b32 v18, v2, v17
	s_waitcnt lgkmcnt(0)
	v_add_f32_e32 v18, v17, v18
	ds_bpermute_b32 v19, v3, v18
	s_waitcnt lgkmcnt(0)
	v_add_f32_e32 v18, v18, v19
	ds_bpermute_b32 v19, v4, v18
	s_waitcnt lgkmcnt(0)
	v_add_f32_e32 v18, v18, v19
	ds_bpermute_b32 v19, v5, v18
	s_waitcnt lgkmcnt(0)
	v_add_f32_e32 v18, v18, v19
	ds_bpermute_b32 v19, v6, v18
	s_waitcnt lgkmcnt(0)
	v_add_f32_e32 v1, v18, v19
	ds_bpermute_b32 v17, v7, v1
	s_waitcnt vmcnt(1)
	v_lshlrev_b32_e32 v35, 16, v35
	v_add_f32_e32 v35, v36, v35
	v_mul_f32_e64 v36, |v35|, s98
	v_exp_f32_e32 v36, v36
	v_min_f32_e32 v35, 0, v35
	v_add_f32_e32 v36, 1.0, v36
	v_log_f32_e32 v36, v36
	s_nop 0
	v_fmac_f32_e32 v35, 0xbf317218, v36
	v_cmp_lt_u32_e32 vcc, s46, v31
	s_nop 1
	v_cndmask_b32_e32 v30, 0, v35, vcc
	s_waitcnt lgkmcnt(0)
	v_add_f32_e32 v1, v1, v17
	ds_bpermute_b32 v17, v8, v30
	v_mul_u32_u24_e32 v29, 0x2080, v29
	s_waitcnt lgkmcnt(0)
	v_add_f32_e32 v17, v30, v17
	v_cndmask_b32_e64 v30, v17, v30, s[72:73]
	ds_bpermute_b32 v17, v9, v30
	v_add_lshl_u32 v31, v31, v29, 2
	s_waitcnt lgkmcnt(0)
	v_add_f32_e32 v17, v30, v17
	v_cndmask_b32_e64 v30, v17, v30, s[74:75]
	ds_bpermute_b32 v17, v10, v30
	s_waitcnt lgkmcnt(0)
	v_add_f32_e32 v17, v30, v17
	v_cndmask_b32_e64 v30, v17, v30, s[76:77]
	ds_bpermute_b32 v17, v11, v30
	s_waitcnt lgkmcnt(0)
	v_add_f32_e32 v17, v30, v17
	v_cndmask_b32_e64 v30, v17, v30, s[78:79]
	ds_bpermute_b32 v17, v12, v30
	s_waitcnt lgkmcnt(0)
	v_add_f32_e32 v17, v30, v17
	v_cndmask_b32_e64 v30, v17, v30, s[80:81]
	ds_bpermute_b32 v17, v13, v30
	s_waitcnt lgkmcnt(0)
	v_add_f32_e32 v17, v30, v17
	v_cndmask_b32_e64 v30, v17, v30, s[82:83]
	v_add_f32_e32 v1, v1, v30
	global_store_dword v31, v1, s[60:61]
.Lfc_noB:
	s_waitcnt vmcnt(0)
	v_add_u32_e32 v14, 0x1000, v14
	s_nop 0
	v_readfirstlane_b32 s6, v14
	s_cmp_le_u32 s6, s37
	s_cbranch_scc1 .Lfc_loop
